# v20 (epilogue-align barrier after the g*u products) + one static s_setprio 1 for waves 4-7 during the stick-breaking attention phases (strategy 4: static priority raise for the younger half)
# speedup vs baseline: 1.0151x; 1.0098x over previous
; __global__ void __launch_bounds__(512, 2) hybrid_fwd(Args a) {
;     ...
;         } else if (k == 4) {
;             if (kind == 0) {
;     ...
;                 sba::phase(lds, ar, ar + (size_t)T * 1024, ar + (size_t)2 * T * 1024, ar + (size_t)3 * T * 1024);
;     ...
;             } else if (kind == 1) {
;                 ssd::Bufs B;
;                 B.z = ar; B.xs_raw = ar + (size_t)T * 2048; B.bc_raw = ar + (size_t)2 * T * 2048; B.ypart = ar + (size_t)3 * T * 2048; B.states = ar + (size_t)4 * T * 2048;
;     ...
;                 B.dt_raw = (const float*)(ws + WS_DT); B.acum = (float*)(ws + WS_ACUM); B.alast = (float*)(ws + WS_ALAST);
;                 B.conv_w = a->in[11]; B.conv_b = a->in[12]; B.dt_bias = a->in[13]; B.a_log = a->in[14]; B.dsk = a->in[15]; B.ng = a->in[16];
;     ...
;                 for (int it = bx; it < NB * NCHUNK * 8; it += G) ssd::s1_item(lds, B, it);
;     ...
;                 ssd::s2_phase(B);
;     ...
;                 ssd::s3_phase(lds, B);
;     ...
;             } else {
;     ...
;                 shortconv_phase(ar, ar + (size_t)T * 1024, ar + (size_t)2 * T * 1024, a->in[19] + (size_t)(layer / 3) * 3 * DM, ar + (size_t)3 * T * 1024);
;     ...
;             }
.LBB0_282:
	s_setprio 0
	s_mov_b32 s40, s79
	s_mov_b64 s[4:5], 0

; __device__ __forceinline__ int tid_l() { int t = threadIdx.x; asm volatile("" : "+v"(t)); return t; }
; #define LAS __attribute__((address_space(3)))
; #define SBA_LOAD(TT) do { const size_t o_ = (size_t)(TT) * 64 * DM; kreg = *(const u32x4*)(kg + o_); kreg2 = *(const u32x4*)(kg + o_ + 8); vreg = *(const u32x4*)(vg + o_); vreg2 = *(const u32x4*)(vg + o_ + 8); } while (0)
; #define SBA_STAGE(BUF) do { LAS unsigned char* bb_ = lds + (BUF) * BUF_BYTES; *(LAS u32x4*)(bb_ + KS_OFF + sc * 1024 + skey * 16) = kreg; *(LAS u32x4*)(bb_ + KS_OFF + (sc + 1) * 1024 + skey * 16) = kreg2; \
;         *(LAS u32x4*)(bb_ + VT_OFF + skey * VT_PITCH + sc * 16) = vreg; *(LAS u32x4*)(bb_ + VT_OFF + skey * VT_PITCH + (sc + 1) * 16) = vreg2; } while (0)
; __device__ __forceinline__ void unit(LAS unsigned char* lds_all, const bf16* Q, const bf16* K, const bf16* V, bf16* O, int b, int hp, int qb) {
;     const int tid = tid_l(), lane = tid & 63, r32 = lane & 31, hi = lane >> 5; const int wid = __builtin_amdgcn_readfirstlane(tid >> 6);
;     const int hf = wid >> 2, h = 2 * hp + hf; LAS unsigned char* lds = lds_all + hf * (2 * BUF_BYTES);
;     const size_t rowbase = (size_t)b * SEQ; const int q0 = qb * 128, qw0 = q0 + (wid & 3) * 32;
;     bf16x8 qr[4];
;     { const bf16* qp = Q + (rowbase + qw0 + r32) * DM + h * 64 + hi * 8;
; #pragma unroll
;       for (int d0 = 0; d0 < 4; ++d0) qr[d0] = *(const bf16x8*)(qp + d0 * 16); }
;     f32x16 o0, o1;
; #pragma unroll
;     for (int r = 0; r < 16; ++r) { o0[r] = 0.f; o1[r] = 0.f; }
;     float carry = 1.0f; bool done = false;
;     const int NT = (q0 + 128) / 64;
;     const int skey = (tid & 255) >> 2, sc = 2 * (tid & 3);
;     const bf16* kg = K + (rowbase + skey) * DM + h * 64 + sc * 8; const bf16* vg = V + (rowbase + skey) * DM + h * 64 + sc * 8;
;     ...
;     u32x4 kreg, kreg2, vreg, vreg2; SBA_LOAD(NT - 1);
;     ...
;     __syncthreads();
;     SBA_STAGE(0);
;     if (NT > 1) SBA_LOAD(NT - 2);
;     __syncthreads();
.LBB0_297:
	v_mov_b32_e32 v20, v200
	s_lshl_b32 s6, s6, 7
	v_readfirstlane_b32 s4, v20
	s_ashr_i32 s9, s4, 6
	s_ashr_i32 s10, s4, 8
	s_cmp_ge_u32 s9, 4
	s_cbranch_scc0 .Lsba_noprio
	s_setprio 1
.Lsba_noprio:
	s_lshl_b32 s4, s2, 6
	s_and_b32 s7, s4, 0x3000
	s_lshl_b32 s4, s9, 5
	s_and_b32 s8, s4, 0x60
	s_or_b32 s18, s8, s6
	v_and_b32_e32 v22, 31, v20
	s_or_b32 s4, s7, s18
	v_or_b32_e32 v23, s4, v22
	s_lshl_b32 s4, s2, 4
	s_and_b32 s4, s4, 0x380
	s_lshl_b32 s5, s10, 6
	s_add_i32 s16, s5, s4
	v_lshlrev_b32_e32 v0, 11, v23
	s_ashr_i32 s17, s16, 31
	v_bfe_u32 v21, v20, 5, 1
	s_waitcnt lgkmcnt(0)
	v_lshl_add_u64 v[2:3], s[0:1], 0, v[0:1]
	s_lshl_b64 s[4:5], s[16:17], 1
	v_lshl_add_u64 v[2:3], v[2:3], 0, s[4:5]
	v_lshlrev_b32_e32 v0, 4, v21
	v_lshl_add_u64 v[18:19], v[2:3], 0, v[0:1]
	v_bfe_u32 v24, v20, 2, 6
	v_lshlrev_b32_e32 v0, 1, v20
	v_and_b32_e32 v25, 6, v0
	v_or_b32_e32 v0, s7, v24
	v_lshlrev_b32_e32 v0, 11, v0
	v_lshl_add_u64 v[2:3], s[40:41], 0, v[0:1]
	s_add_i32 s19, s6, 0x80
	v_lshl_add_u64 v[2:3], v[2:3], 0, s[4:5]
	v_lshlrev_b32_e32 v98, 4, v25
	v_mov_b32_e32 v99, v1
	s_lshr_b32 s6, s19, 6
	v_lshl_add_u64 v[100:101], v[2:3], 0, v[98:99]
	v_lshl_add_u64 v[2:3], s[36:37], 0, v[0:1]
	v_lshl_add_u64 v[2:3], v[2:3], 0, s[4:5]
	s_add_i32 s88, s6, -1
	v_lshl_add_u64 v[102:103], v[2:3], 0, v[98:99]
	s_lshl_b64 s[4:5], s[88:89], 17
	v_lshl_add_u64 v[6:7], v[100:101], 0, s[4:5]
	v_lshl_add_u64 v[14:15], v[102:103], 0, s[4:5]
	s_mov_b32 s7, s89
	s_add_i32 s6, s6, -2
	global_load_dwordx4 v[2:5], v[6:7], off offset:16
	s_nop 0
	global_load_dwordx4 v[6:9], v[6:7], off
	s_nop 0
	global_load_dwordx4 v[10:13], v[14:15], off
	s_nop 0
	global_load_dwordx4 v[14:17], v[14:15], off offset:16
	s_lshl_b64 s[6:7], s[6:7], 17
	v_and_b32_e32 v0, 63, v20
	v_lshrrev_b32_e32 v26, 2, v20
	v_and_b32_e32 v27, 16, v20
	v_lshlrev_b32_e32 v20, 2, v20
	global_load_dwordx4 v[66:69], v[18:19], off
	global_load_dwordx4 v[70:73], v[18:19], off offset:32
	global_load_dwordx4 v[74:77], v[18:19], off offset:64
	global_load_dwordx4 v[78:81], v[18:19], off offset:96
	v_lshl_add_u64 v[18:19], v[102:103], 0, s[6:7]
	v_lshlrev_b32_e32 v133, 10, v21
	v_lshlrev_b32_e32 v99, 2, v21
	v_and_or_b32 v27, v20, 12, v27
	v_lshl_add_u64 v[20:21], v[100:101], 0, s[6:7]
	s_barrier
	global_load_dwordx4 v[90:93], v[18:19], off offset:16
	global_load_dwordx4 v[94:97], v[18:19], off
	global_load_dwordx4 v[82:85], v[20:21], off offset:16
	global_load_dwordx4 v[86:89], v[20:21], off
	s_mul_i32 s10, s10, 0xa000
	s_add_i32 s20, s10, 0
	v_lshlrev_b32_e32 v105, 4, v24
	v_lshlrev_b32_e32 v135, 10, v25
	v_or_b32_e32 v18, 1, v25
	v_mov_b32_e32 v20, s20
	s_movk_i32 s6, 0xc0
	v_and_or_b32 v19, v26, 3, v99
	v_lshlrev_b32_e32 v136, 10, v18
	v_lshlrev_b32_e32 v137, 4, v18
	v_add3_u32 v18, s20, v135, v105
	v_mad_u32_u24 v20, v24, s6, v20
	v_mul_u32_u24_e32 v138, 0xc0, v19
	v_add3_u32 v19, s20, v136, v105
	v_add_u32_e32 v21, v20, v98
	v_add_u32_e32 v20, v20, v137
	s_sub_i32 s8, s8, 64
	v_mul_u32_u24_e32 v132, 0xc0, v24
	v_lshlrev_b32_e32 v134, 4, v22
	v_cmp_gt_u32_e64 s[4:5], 32, v0
	v_lshlrev_b32_e32 v104, 10, v23
	v_lshlrev_b32_e32 v139, 1, v27
	v_cmp_eq_u32_e64 s[6:7], 0, v0
	s_lshl_b32 s9, s9, 2
	v_or_b32_e32 v184, s8, v22
	v_mov_b32_e32 v0, v1
	s_add_i32 s21, s9, 0
	s_add_i32 s21, s21, 0x14000
	v_or_b32_e32 v140, 56, v99
	v_or_b32_e32 v141, 57, v99
	v_or_b32_e32 v142, 58, v99
	v_or_b32_e32 v143, 59, v99
	v_or_b32_e32 v144, 48, v99
	v_or_b32_e32 v145, 49, v99
	v_or_b32_e32 v146, 50, v99
	v_or_b32_e32 v147, 51, v99
	v_or_b32_e32 v148, 40, v99
	v_or_b32_e32 v149, 41, v99
	s_waitcnt vmcnt(10)
	ds_write_b128 v18, v[6:9]
	ds_write_b128 v19, v[2:5]
	s_waitcnt vmcnt(9)
	ds_write_b128 v21, v[10:13] offset:8192
	s_waitcnt vmcnt(8)
	ds_write_b128 v20, v[14:17] offset:8192
	v_mov_b32_e32 v14, v1
	v_mov_b32_e32 v15, v1
	v_mov_b32_e32 v2, v1
	v_mov_b32_e32 v3, v1
	v_mov_b32_e32 v4, v1
	v_mov_b32_e32 v5, v1
	v_mov_b32_e32 v6, v1
	v_mov_b32_e32 v7, v1
	v_mov_b32_e32 v8, v1
	v_mov_b32_e32 v9, v1
	v_mov_b32_e32 v10, v1
	v_mov_b32_e32 v11, v1
	v_mov_b32_e32 v12, v1
	v_mov_b32_e32 v13, v1
	v_mov_b64_e32 v[32:33], v[14:15]
	v_mov_b64_e32 v[30:31], v[12:13]
	v_mov_b64_e32 v[28:29], v[10:11]
	v_mov_b64_e32 v[26:27], v[8:9]
	v_mov_b64_e32 v[24:25], v[6:7]
	v_mov_b64_e32 v[22:23], v[4:5]
	v_mov_b64_e32 v[20:21], v[2:3]
	v_mov_b64_e32 v[18:19], v[0:1]
	v_mov_b64_e32 v[16:17], v[14:15]
	v_or_b32_e32 v150, 42, v99
	v_or_b32_e32 v151, 43, v99
	v_or_b32_e32 v152, 32, v99
	v_or_b32_e32 v153, 33, v99
	v_or_b32_e32 v154, 34, v99
	v_or_b32_e32 v155, 35, v99
	v_or_b32_e32 v156, 24, v99
	v_or_b32_e32 v157, 25, v99
	v_or_b32_e32 v165, 26, v99
	v_or_b32_e32 v172, 27, v99
	v_or_b32_e32 v173, 16, v99
	v_or_b32_e32 v174, 17, v99
	v_or_b32_e32 v175, 18, v99
	v_or_b32_e32 v176, 19, v99
	v_or_b32_e32 v177, 8, v99
	v_or_b32_e32 v178, 9, v99
	v_or_b32_e32 v179, 10, v99
	v_or_b32_e32 v180, 11, v99
	v_or_b32_e32 v181, 1, v99
	v_or_b32_e32 v182, 2, v99
	v_or_b32_e32 v183, 3, v99
	s_mov_b64 s[8:9], 0
	v_mov_b32_e32 v109, 1.0
	v_mov_b64_e32 v[14:15], v[12:13]
	v_mov_b64_e32 v[12:13], v[10:11]
	v_mov_b64_e32 v[10:11], v[8:9]
	v_mov_b64_e32 v[8:9], v[6:7]
	v_mov_b64_e32 v[6:7], v[4:5]
	v_mov_b64_e32 v[4:5], v[2:3]
	v_mov_b64_e32 v[2:3], v[0:1]
	s_mov_b32 s23, s88
	s_waitcnt lgkmcnt(0)
	s_barrier
